# attention: deferred waves issue next tile K-fragment LDS reads before their deferred PV; P(hh0) moved out of K-fragment registers
# baseline (speedup 1.0000x reference)
; #define LAS __attribute__((address_space(3)))
; DEV void attn_tile(LAS unsigned char* lds, const bf16x8 (&qf)[2][2], int tl, int kpos0, int mode, bool near, bool rowsel, const float (&cbias)[2],
;                    unsigned kb, unsigned vb_, unsigned btb, int g4, float (&mrun)[2], float (&lrun)[2], f32x4 (&O)[2][4]) {
;     f32x4 sc[2][4];
;     float ci[2];
; #pragma unroll
;     for (int hh = 0; hh < 2; ++hh) { const float mne = mrun[hh] < -1e29f ? 0.f : mrun[hh];
;         ci[hh] = near ? -mne : (((mode == 1 && !rowsel) ? NEG_ : cbias[hh]) - mne); }
;     {
;         bf16x8 kf[4][2];
; #pragma unroll
;         for (int kt = 0; kt < 4; ++kt) { kf[kt][0] = *(const LAS bf16x8*)(lds + kb + kt * 2304); kf[kt][1] = *(const LAS bf16x8*)(lds + kb + kt * 2304 + 64); }
;         __builtin_amdgcn_sched_barrier(0);
; #pragma unroll
;         for (int kt = 0; kt < 4; ++kt)
; #pragma unroll
;             for (int hh = 0; hh < 2; ++hh) sc[hh][kt] = __builtin_amdgcn_mfma_f32_16x16x32_bf16(kf[kt][0], qf[hh][0], (f32x4){ci[hh], ci[hh], ci[hh], ci[hh]}, 0, 0, 0);
; #pragma unroll
;         for (int kt = 0; kt < 4; ++kt)
; #pragma unroll
;             for (int hh = 0; hh < 2; ++hh) sc[hh][kt] = __builtin_amdgcn_mfma_f32_16x16x32_bf16(kf[kt][1], qf[hh][1], sc[hh][kt], 0, 0, 0);
;     }
.Lst_xx:
	s_mov_b32 s101, s99
	s_cmp_ge_i32 s50, s36
	s_cselect_b64 s[4:5], -1, 0
	s_cmp_eq_u32 s97, 2
	s_cselect_b64 s[6:7], -1, 0
	s_cmp_eq_u32 s50, s17
	s_cselect_b64 s[42:43], -1, 0
	s_and_b64 s[6:7], s[6:7], s[42:43]
	s_or_b64 s[4:5], s[4:5], s[6:7]
	v_lshrrev_b32_e32 v64, s50, v127
	v_and_b32_e32 v64, 1, v64
	s_cmp_lg_u32 s97, 1
	v_cmp_eq_u32_e64 s[48:49], 1, v64
	s_cselect_b64 s[6:7], -1, 0
	s_or_b64 vcc, s[6:7], s[48:49]
	v_cmp_gt_f32_e64 s[44:45], s65, v149
	v_cndmask_b32_e32 v65, v223, v136, vcc
	v_cmp_gt_f32_e64 s[42:43], s65, v150
	v_cndmask_b32_e64 v64, v149, 0, s[44:45]
	v_sub_f32_e32 v65, v65, v64
	v_cndmask_b32_e64 v64, v65, -v64, s[4:5]
	v_cndmask_b32_e64 v65, v150, 0, s[42:43]
	v_cndmask_b32_e32 v66, v223, v137, vcc
	v_sub_f32_e32 v66, v66, v65
	v_cndmask_b32_e64 v68, v66, -v65, s[4:5]
	s_cmp_eq_u32 s100, 1
	s_cbranch_scc1 .Lst_kskip
	v_add_u32_e32 v65, s98, v141
	ds_read_b128 v[72:75], v65
	ds_read_b128 v[76:79], v65 offset:64
	ds_read_b128 v[80:83], v65 offset:2304
	ds_read_b128 v[84:87], v65 offset:2368
	ds_read_b128 v[88:91], v65 offset:4608
	ds_read_b128 v[154:157], v65 offset:4672
	ds_read_b128 v[92:95], v65 offset:6912
	ds_read_b128 v[158:161], v65 offset:6976
.Lst_kskip:
	v_mov_b32_e32 v65, v64
	v_mov_b32_e32 v66, v64
	v_mov_b32_e32 v67, v64
	v_mov_b32_e32 v69, v68
	v_mov_b32_e32 v70, v68
	v_mov_b32_e32 v71, v68
	s_waitcnt lgkmcnt(7)
	v_mfma_f32_16x16x32_bf16 v[162:165], v[72:75], v[8:11], v[64:67]
	s_mov_b64 s[6:7], -1
	s_and_b64 vcc, exec, s[4:5]
	v_mfma_f32_16x16x32_bf16 v[72:75], v[72:75], v[16:19], v[68:71]
	v_add_u32_e32 v228, s98, v145
	v_add_u32_e32 v229, 0x800, v228
	v_add_u32_e32 v230, 0x1000, v228
	v_add_u32_e32 v231, 0x1800, v228
	ds_read2_b64 v[232:235], v228 offset1:4
	ds_read2_b64 v[236:239], v228 offset0:8 offset1:12
	ds_read2_b64 v[240:243], v229 offset0:32 offset1:36
	ds_read2_b64 v[244:247], v229 offset0:40 offset1:44
	ds_read2_b64 v[248:251], v230 offset0:64 offset1:68
	ds_read2_b64 v[198:201], v230 offset0:72 offset1:76
	ds_read2_b64 v[202:205], v231 offset0:96 offset1:100
	ds_read2_b64 v[206:209], v231 offset0:104 offset1:108
	s_waitcnt lgkmcnt(13)
	v_mfma_f32_16x16x32_bf16 v[166:169], v[80:83], v[8:11], v[64:67]
	v_mfma_f32_16x16x32_bf16 v[80:83], v[80:83], v[16:19], v[68:71]
	s_waitcnt lgkmcnt(11)
	v_mfma_f32_16x16x32_bf16 v[180:183], v[88:91], v[8:11], v[64:67]
	v_mfma_f32_16x16x32_bf16 v[184:187], v[88:91], v[16:19], v[68:71]
	s_waitcnt lgkmcnt(9)
	v_mfma_f32_16x16x32_bf16 v[188:191], v[92:95], v[8:11], v[64:67]
	v_mfma_f32_16x16x32_bf16 v[68:71], v[92:95], v[16:19], v[68:71]
	v_mfma_f32_16x16x32_bf16 v[92:95], v[76:79], v[12:15], v[162:165]
	v_mfma_f32_16x16x32_bf16 v[76:79], v[76:79], v[20:23], v[72:75]
	v_mfma_f32_16x16x32_bf16 v[88:91], v[84:87], v[12:15], v[166:169]
	v_mfma_f32_16x16x32_bf16 v[72:75], v[84:87], v[20:23], v[80:83]
	v_mfma_f32_16x16x32_bf16 v[84:87], v[154:157], v[12:15], v[180:183]
	v_mfma_f32_16x16x32_bf16 v[64:67], v[154:157], v[20:23], v[184:187]
	s_waitcnt lgkmcnt(8)
	v_mfma_f32_16x16x32_bf16 v[80:83], v[158:161], v[12:15], v[188:191]
	v_mfma_f32_16x16x32_bf16 v[68:71], v[158:161], v[20:23], v[68:71]
	s_cbranch_vccnz .LBB0_271
	s_mov_b64 s[6:7], 0

; #define LAS __attribute__((address_space(3)))
; #define OPQV(x) asm volatile("" : "+v"(x))
; DEV void kv_store(LAS unsigned char* lds, const KVRegs& r, int buf, int tid) {
;     const int key = tid >> 3, c8 = (tid & 7) * 8;
;     unsigned kw = AT_KS + buf * 9216 + (key * 72 + c8) * 2, vw = AT_VT + buf * 9216 + ((tid >> 6) * 8 * 72 + (tid & 63)) * 2; OPQV(kw); OPQV(vw);
;     *(LAS u32x4*)(lds + kw) = r.k;
; #pragma unroll
;     for (int j = 0; j < 4; ++j) { *(LAS bf16_t*)(lds + vw + j * 288) = (bf16_t)(r.v[j] & 0xffffu); *(LAS bf16_t*)(lds + vw + j * 288 + 144) = (bf16_t)(r.v[j] >> 16); }
; }
; DEV void attn_item(LAS unsigned char* lds, const bf16_t* P, const bf16_t* QB, const bf16_t* KV, const bf16_t* KC, const bf16_t* VC, const float* rel_bias, bf16_t* OB, int b, int g, int qt) {
;     ...
;             kv_store(lds, pre, buf, tid);
;             __syncthreads();
.Lst_zz:
	s_min_u32 s100, s100, 1
	s_andn2_b64 vcc, exec, s[92:93]
	s_cbranch_vccz .Lst_exit
	s_xor_b32 s98, s98, 0x2400
	v_add_u32_e32 v228, s98, v139
	v_add_u32_e32 v229, s98, v146
	s_waitcnt vmcnt(1)
	ds_write_b128 v228, v[24:27]
	s_waitcnt vmcnt(0)
	ds_write_b16 v229, v28
	ds_write_b16_d16_hi v229, v28 offset:144
	ds_write_b16 v229, v29 offset:288
	ds_write_b16_d16_hi v229, v29 offset:432
	ds_write_b16 v229, v30 offset:576
	ds_write_b16_d16_hi v229, v30 offset:720
	ds_write_b16 v229, v31 offset:864
	ds_write_b16_d16_hi v229, v31 offset:1008
	s_waitcnt lgkmcnt(0)
	s_barrier
	s_mov_b32 s97, s96
	s_mov_b32 s50, s52
	s_branch .LBB0_260

; #define LAS __attribute__((address_space(3)))
; DEV unsigned cvt_pk_bf16(float lo, float hi) { unsigned r; asm volatile("v_cvt_pk_bf16_f32 %0, %1, %2" : "=v"(r) : "v"(lo), "v"(hi)); return r; }
; DEV void attn_tile(LAS unsigned char* lds, const bf16x8 (&qf)[2][2], int tl, int kpos0, int mode, bool near, bool rowsel, const float (&cbias)[2],
;                    unsigned kb, unsigned vb_, unsigned btb, int g4, float (&mrun)[2], float (&lrun)[2], f32x4 (&O)[2][4]) {
;     ...
;         float rs = 0.f;
; #pragma unroll
;         for (int kt = 0; kt < 4; ++kt)
; #pragma unroll
;             for (int r = 0; r < 4; ++r) { const float p = __builtin_amdgcn_exp2f(sc[hh][kt][r]); sc[hh][kt][r] = p; rs += p; }
;         lrun[hh] += rs;
; #pragma unroll
;         for (int kc = 0; kc < 2; ++kc) { u32x4 w; w.x = cvt_pk_bf16(sc[hh][2 * kc][0], sc[hh][2 * kc][1]); w.y = cvt_pk_bf16(sc[hh][2 * kc][2], sc[hh][2 * kc][3]);
;             w.z = cvt_pk_bf16(sc[hh][2 * kc + 1][0], sc[hh][2 * kc + 1][1]); w.w = cvt_pk_bf16(sc[hh][2 * kc + 1][2], sc[hh][2 * kc + 1][3]); pf[hh][kc] = as_bf16x8(w); }
;     }
; #pragma unroll
;     for (int dt = 0; dt < 4; ++dt)
; #pragma unroll
;         for (int kc = 0; kc < 2; ++kc) {
;             const u32x2 va = *(const LAS u32x2*)(lds + vb_ + dt * 2304 + kc * 64);
;             const u32x2 vb = *(const LAS u32x2*)(lds + vb_ + dt * 2304 + kc * 64 + 32);
;             const bf16x8 vf = as_bf16x8((u32x4){va.x, va.y, vb.x, vb.y});
; #pragma unroll
;             for (int hh = 0; hh < 2; ++hh) O[hh][dt] = __builtin_amdgcn_mfma_f32_16x16x32_bf16(vf, pf[hh][kc], O[hh][dt], 0, 0, 0);
;         }
; }
.Lst_y_entry:
	v_exp_f32_e32 v92, v92
	v_exp_f32_e32 v93, v93
	v_exp_f32_e32 v94, v94
	v_exp_f32_e32 v95, v95
	v_exp_f32_e32 v88, v88
	v_exp_f32_e32 v89, v89
	v_exp_f32_e32 v90, v90
	v_exp_f32_e32 v91, v91
	v_exp_f32_e32 v153, v84
	v_exp_f32_e32 v154, v85
	v_exp_f32_e32 v155, v86
	v_exp_f32_e32 v156, v87
	v_exp_f32_e32 v157, v80
	v_exp_f32_e32 v158, v81
	v_exp_f32_e32 v159, v82
	v_exp_f32_e32 v160, v83
	v_cvt_pk_bf16_f32 v162, v92, v93
	v_cvt_pk_bf16_f32 v163, v94, v95
	v_cvt_pk_bf16_f32 v164, v88, v89
	v_cvt_pk_bf16_f32 v165, v90, v91
	v_cvt_pk_bf16_f32 v166, v153, v154
	v_cvt_pk_bf16_f32 v167, v155, v156
	v_cvt_pk_bf16_f32 v168, v157, v158
	v_cvt_pk_bf16_f32 v169, v159, v160
	v_add_f32_e32 v92, 0, v92
	v_add_f32_e32 v92, v93, v92
	v_add_f32_e32 v92, v94, v92
	v_add_f32_e32 v92, v95, v92
	v_add_f32_e32 v88, v88, v92
	v_add_f32_e32 v88, v89, v88
	v_add_f32_e32 v88, v90, v88
	v_add_f32_e32 v88, v91, v88
	v_add_f32_e32 v88, v153, v88
	v_add_f32_e32 v88, v154, v88
	v_add_f32_e32 v88, v155, v88
	v_add_f32_e32 v88, v156, v88
	v_add_f32_e32 v88, v157, v88
	v_exp_f32_e32 v76, v76
	v_add_f32_e32 v88, v158, v88
	v_exp_f32_e32 v77, v77
	v_add_f32_e32 v88, v159, v88
	v_exp_f32_e32 v78, v78
	v_add_f32_e32 v88, v160, v88
	v_exp_f32_e32 v79, v79
	v_add_f32_e32 v151, v151, v88
	v_add_f32_e32 v88, 0, v76
	v_exp_f32_e32 v72, v72
	v_add_f32_e32 v88, v77, v88
	v_exp_f32_e32 v73, v73
	v_add_f32_e32 v88, v78, v88
	v_exp_f32_e32 v74, v74
	v_add_f32_e32 v88, v79, v88
	v_exp_f32_e32 v75, v75
	v_add_f32_e32 v88, v72, v88
	v_exp_f32_e32 v64, v64
	v_add_f32_e32 v88, v73, v88
	v_exp_f32_e32 v65, v65
	v_add_f32_e32 v88, v74, v88
	v_exp_f32_e32 v66, v66
	v_add_f32_e32 v88, v75, v88
	v_exp_f32_e32 v67, v67
	v_add_f32_e32 v88, v64, v88
	v_exp_f32_e32 v89, v68
	v_add_f32_e32 v88, v65, v88
	v_add_f32_e32 v88, v66, v88
	v_add_f32_e32 v88, v67, v88
	v_add_f32_e32 v68, v89, v88
	v_exp_f32_e32 v88, v69
	v_exp_f32_e32 v90, v70
	v_exp_f32_e32 v91, v71
	v_add_f32_e32 v68, v88, v68
	v_add_f32_e32 v68, v90, v68
	v_add_f32_e32 v68, v91, v68
	v_add_f32_e32 v148, v148, v68
	v_cvt_pk_bf16_f32 v68, v76, v77
	v_cvt_pk_bf16_f32 v69, v78, v79
	v_cvt_pk_bf16_f32 v70, v72, v73
	v_cvt_pk_bf16_f32 v71, v74, v75
	v_cvt_pk_bf16_f32 v64, v64, v65
	v_cvt_pk_bf16_f32 v65, v66, v67
	v_cvt_pk_bf16_f32 v66, v89, v88
	v_cvt_pk_bf16_f32 v67, v90, v91
	s_cmp_eq_u32 s100, 1
	s_cbranch_scc0 .Lst_nokpre
	v_add_u32_e32 v228, s98, v141
	ds_read_b128 v[72:75], v228
	ds_read_b128 v[76:79], v228 offset:64
	ds_read_b128 v[80:83], v228 offset:2304
	ds_read_b128 v[84:87], v228 offset:2368
	ds_read_b128 v[88:91], v228 offset:4608
	ds_read_b128 v[154:157], v228 offset:4672
	ds_read_b128 v[92:95], v228 offset:6912
	ds_read_b128 v[158:161], v228 offset:6976
.Lst_nokpre:
	s_waitcnt lgkmcnt(7)
	v_mfma_f32_16x16x32_bf16 v[44:47], v[232:235], v[162:165], v[44:47]
	v_mfma_f32_16x16x32_bf16 v[32:35], v[232:235], v[68:71], v[32:35]
	s_waitcnt lgkmcnt(6)
	v_mfma_f32_16x16x32_bf16 v[44:47], v[236:239], v[166:169], v[44:47]
	v_mfma_f32_16x16x32_bf16 v[32:35], v[236:239], v[64:67], v[32:35]
	s_waitcnt lgkmcnt(5)
	v_mfma_f32_16x16x32_bf16 v[56:59], v[240:243], v[162:165], v[56:59]
	v_mfma_f32_16x16x32_bf16 v[40:43], v[240:243], v[68:71], v[40:43]
	s_waitcnt lgkmcnt(4)
	v_mfma_f32_16x16x32_bf16 v[56:59], v[244:247], v[166:169], v[56:59]
	v_mfma_f32_16x16x32_bf16 v[40:43], v[244:247], v[64:67], v[40:43]
	s_waitcnt lgkmcnt(3)
	v_mfma_f32_16x16x32_bf16 v[52:55], v[248:251], v[162:165], v[52:55]
	v_mfma_f32_16x16x32_bf16 v[36:39], v[248:251], v[68:71], v[36:39]
	s_waitcnt lgkmcnt(2)
	v_mfma_f32_16x16x32_bf16 v[52:55], v[198:201], v[166:169], v[52:55]
	v_mfma_f32_16x16x32_bf16 v[36:39], v[198:201], v[64:67], v[36:39]
	s_waitcnt lgkmcnt(1)
	v_mfma_f32_16x16x32_bf16 v[48:51], v[202:205], v[68:71], v[48:51]
	v_mfma_f32_16x16x32_bf16 v[60:63], v[202:205], v[162:165], v[60:63]
	s_waitcnt lgkmcnt(0)
	v_mfma_f32_16x16x32_bf16 v[60:63], v[206:209], v[166:169], v[60:63]
	v_mfma_f32_16x16x32_bf16 v[48:51], v[206:209], v[64:67], v[48:51]
	s_bitcmp1_b32 s101, 8
	s_cbranch_scc0 .LBB0_283
	ds_bpermute_b32 v64, v143, v151
	s_and_b32 s6, s101, 0xff
	s_lshl_b32 s6, s6, 1
	v_mov_b32_e32 v66, 0
	s_waitcnt lgkmcnt(0)
	v_add_f32_e32 v64, v151, v64
	ds_bpermute_b32 v65, v144, v64
	s_waitcnt lgkmcnt(0)
	v_add_f32_e32 v65, v64, v65
	v_mov_b32_e32 v64, 0
	v_cmp_lt_f32_e32 vcc, 0, v65
	s_and_saveexec_b64 s[4:5], vcc
	s_cbranch_execz .LBB0_280
	s_cmp_eq_u32 s6, 1
	s_cselect_b64 vcc, -1, 0
	s_cmp_eq_u32 s6, 2
	v_cndmask_b32_e32 v66, v126, v7, vcc
	s_cselect_b64 vcc, -1, 0
	s_cmp_eq_u32 s6, 3
	v_cndmask_b32_e32 v66, v66, v2, vcc
	s_cselect_b64 vcc, -1, 0
	s_cmp_eq_u32 s6, 4
	v_cndmask_b32_e32 v66, v66, v3, vcc
	s_cselect_b64 vcc, -1, 0
	s_cmp_eq_u32 s6, 5
	v_cndmask_b32_e32 v66, v66, v4, vcc
	s_cselect_b64 vcc, -1, 0
	v_cndmask_b32_e32 v66, v66, v5, vcc
	v_div_scale_f32 v67, s[42:43], v65, v65, v66
	v_rcp_f32_e32 v68, v67
	s_nop 0
	v_fma_f32 v69, -v67, v68, 1.0
	v_fmac_f32_e32 v68, v69, v68
	v_div_scale_f32 v69, vcc, v66, v65, v66
	v_mul_f32_e32 v70, v69, v68
	v_fma_f32 v71, -v67, v70, v69
	v_fmac_f32_e32 v70, v71, v68
	v_fma_f32 v67, -v67, v70, v69
	v_div_fmas_f32 v67, v67, v68, v70
	v_div_fixup_f32 v66, v67, v65, v66
